# neighbourhood-attention latent unit hand-rewritten: own prologue (bias table loads batched), 40-live-element tiles with literal lane masks, S/VALU/PV interleave, counted lgkmcnt/vmcnt; on top of the d
# speedup vs baseline: 1.0534x; 1.0132x over previous
.LBB0_502:
	s_and_b64 vcc, exec, s[0:1]
	s_cbranch_vccz .LBB0_489
	s_lshl_b32 s0, s16, 4
	s_and_b32 s0, s0, 0x70
	s_bfe_u32 s1, s16, 0x40003
	s_or_b32 s4, s0, s1
	s_ashr_i32 s5, s16, 7
	s_max_i32 s6, s4, 4
	s_min_i32 s6, s6, 0x7c
	s_add_i32 s6, s6, -4
	s_lshl_b32 s7, s5, 13
	s_lshl_b32 s8, s4, 6
	s_add_i32 s8, s8, s7
	s_lshl_b32 s9, s6, 6
	s_add_i32 s9, s9, s7
	s_lshl_b32 s17, s5, 8
	s_add_i32 s17, s17, 0x4000
	v_readlane_b32 s10, v251, 44
	v_readlane_b32 s14, v255, 16
	v_readlane_b32 s15, v255, 17
	v_readlane_b32 s18, v255, 12
	v_readlane_b32 s19, v255, 13
	v_mbcnt_lo_u32_b32 v237, -1, 0
	v_mbcnt_hi_u32_b32 v237, -1, v237
	s_lshr_b32 s10, s10, 6
	v_and_b32_e32 v238, 31, v237
	v_lshrrev_b32_e32 v239, 5, v237
	s_sub_i32 s11, s6, s4
	s_add_i32 s11, s11, 7
	s_mul_i32 s12, s10, 15
	s_add_i32 s11, s11, s12
	v_add_u32_e32 v240, s11, v239
	v_min_u32_e32 v241, 30, v238
	v_mad_u32_u24 v240, v240, 31, v241
	v_lshlrev_b32_e32 v240, 2, v240
	global_load_dword v242, v240, s[14:15]
	global_load_dword v243, v240, s[14:15] offset:248
	global_load_dword v244, v240, s[14:15] offset:496
	global_load_dword v245, v240, s[14:15] offset:744
	v_add_u32_e32 v180, s8, v238
	v_mov_b32_e32 v181, 0
	v_mov_b32_e32 v177, 0
	v_add_u32_e32 v176, 32, v180
	v_lshlrev_b32_e32 v174, 2, v239
	v_lshlrev_b32_e32 v246, 4, v239
	v_mov_b32_e32 v247, 0
	v_lshl_add_u64 v[246:247], v[246:247], 0, s[18:19]
	v_mad_i64_i32 v[248:249], s[0:1], v180, s71, v[246:247]
	v_mad_i64_i32 v[246:247], s[0:1], v176, s71, v[246:247]
	global_load_dwordx4 v[128:131], v[248:249], off
	global_load_dwordx4 v[132:135], v[248:249], off offset:32
	global_load_dwordx4 v[136:139], v[248:249], off offset:64
	global_load_dwordx4 v[140:143], v[248:249], off offset:96
	global_load_dwordx4 v[144:147], v[246:247], off
	global_load_dwordx4 v[148:151], v[246:247], off offset:32
	global_load_dwordx4 v[152:155], v[246:247], off offset:64
	global_load_dwordx4 v[156:159], v[246:247], off offset:96
	s_mul_i32 s12, s9, 0x1200
	s_add_u32 s20, s18, s12
	s_addc_u32 s21, s19, 0
	s_add_u32 s22, s20, 0x800
	s_addc_u32 s23, s21, 0
	s_add_u32 s20, s20, 0x400
	s_addc_u32 s21, s21, 0
	v_lshrrev_b32_e32 v214, 3, v237
	v_mul_u32_u24_e32 v214, 0x1200, v214
	v_lshrrev_b32_e32 v215, 4, v237
	v_xor_b32_e32 v215, v215, v237
	v_and_b32_e32 v215, 7, v215
	v_lshl_add_u32 v234, v215, 4, v214
	v_xor_b32_e32 v235, 64, v234
	v_lshrrev_b32_e32 v214, 2, v238
	v_mul_u32_u24_e32 v214, 0x1200, v214
	v_lshl_add_u32 v214, v239, 6, v214
	v_and_b32_e32 v215, 3, v237
	v_lshl_add_u32 v236, v215, 4, v214
	s_add_i32 m0, s87, 0x2000
	s_nop 0
	global_load_lds_dwordx4 v234, s[20:21]
	s_add_i32 m0, s87, 0x2400
	s_add_u32 s28, s20, 0x9000
	s_addc_u32 s29, s21, 0
	global_load_lds_dwordx4 v235, s[28:29]
	s_add_i32 m0, s87, 0x2800
	s_add_u32 s28, s20, 0x12000
	s_addc_u32 s29, s21, 0
	global_load_lds_dwordx4 v234, s[28:29]
	s_add_i32 m0, s87, 0x2c00
	s_add_u32 s28, s20, 0x1b000
	s_addc_u32 s29, s21, 0
	global_load_lds_dwordx4 v235, s[28:29]
	s_add_i32 m0, s87, 0x3000
	s_add_u32 s28, s20, 0x24000
	s_addc_u32 s29, s21, 0
	global_load_lds_dwordx4 v234, s[28:29]
	s_add_i32 m0, s87, 0x3400
	s_add_u32 s28, s20, 0x2d000
	s_addc_u32 s29, s21, 0
	global_load_lds_dwordx4 v235, s[28:29]
	s_add_i32 m0, s87, 0x3800
	s_add_u32 s28, s20, 0x36000
	s_addc_u32 s29, s21, 0
	global_load_lds_dwordx4 v234, s[28:29]
	s_add_i32 m0, s87, 0x3c00
	s_add_u32 s28, s20, 0x3f000
	s_addc_u32 s29, s21, 0
	global_load_lds_dwordx4 v235, s[28:29]
	s_mov_b32 m0, s87
	s_nop 0
	global_load_lds_dwordx4 v236, s[22:23]
	s_add_i32 m0, s87, 0x400
	s_add_u32 s28, s22, 0x9000
	s_addc_u32 s29, s23, 0
	global_load_lds_dwordx4 v236, s[28:29]
	s_add_i32 m0, s87, 0x800
	s_add_u32 s28, s22, 0x12000
	s_addc_u32 s29, s23, 0
	global_load_lds_dwordx4 v236, s[28:29]
	s_add_i32 m0, s87, 0xc00
	s_add_u32 s28, s22, 0x1b000
	s_addc_u32 s29, s23, 0
	global_load_lds_dwordx4 v236, s[28:29]
	s_add_i32 m0, s87, 0x1000
	s_add_u32 s28, s22, 0x24000
	s_addc_u32 s29, s23, 0
	global_load_lds_dwordx4 v236, s[28:29]
	s_add_i32 m0, s87, 0x1400
	s_add_u32 s28, s22, 0x2d000
	s_addc_u32 s29, s23, 0
	global_load_lds_dwordx4 v236, s[28:29]
	s_add_i32 m0, s87, 0x1800
	s_add_u32 s28, s22, 0x36000
	s_addc_u32 s29, s23, 0
	global_load_lds_dwordx4 v236, s[28:29]
	s_add_i32 m0, s87, 0x1c00
	s_add_u32 s28, s22, 0x3f000
	s_addc_u32 s29, s23, 0
	global_load_lds_dwordx4 v236, s[28:29]
	v_lshlrev_b32_e32 v214, 7, v238
	v_add_u32_e32 v214, s87, v214
	v_lshrrev_b32_e32 v215, 1, v237
	v_mov_b32_e32 v219, v239
	v_xor_b32_e32 v219, v219, v215
	v_and_b32_e32 v219, 7, v219
	v_lshl_add_u32 v228, v219, 4, v214
	v_add_u32_e32 v219, 2, v239
	v_xor_b32_e32 v219, v219, v215
	v_and_b32_e32 v219, 7, v219
	v_lshl_add_u32 v229, v219, 4, v214
	v_add_u32_e32 v219, 4, v239
	v_xor_b32_e32 v219, v219, v215
	v_and_b32_e32 v219, 7, v219
	v_lshl_add_u32 v230, v219, 4, v214
	v_add_u32_e32 v219, 6, v239
	v_xor_b32_e32 v219, v219, v215
	v_and_b32_e32 v219, 7, v219
	v_lshl_add_u32 v231, v219, 4, v214
	v_lshrrev_b32_e32 v214, 2, v237
	v_and_b32_e32 v214, 3, v214
	v_lshl_or_b32 v214, v239, 2, v214
	v_lshlrev_b32_e32 v214, 6, v214
	v_lshlrev_b32_e32 v215, 1, v237
	v_and_b32_e32 v215, 32, v215
	v_and_b32_e32 v219, 3, v237
	v_lshlrev_b32_e32 v219, 3, v219
	v_add3_u32 v232, v214, v215, v219
	v_add_u32_e32 v232, s87, v232
	v_lshlrev_b32_e32 v214, 4, v239
	v_lshlrev_b32_e32 v215, 2, v238
	v_sub_u32_e32 v214, v214, v215
	s_add_i32 s12, s87, 0x3fbc
	v_add_u32_e32 v233, s12, v214
	v_mov_b32_e32 v0, 0
	v_mov_b32_e32 v1, 0
	v_mov_b32_e32 v2, 0
	v_mov_b32_e32 v3, 0
	v_mov_b32_e32 v4, 0
	v_mov_b32_e32 v5, 0
	v_mov_b32_e32 v6, 0
	v_mov_b32_e32 v7, 0
	v_mov_b32_e32 v8, 0
	v_mov_b32_e32 v9, 0
	v_mov_b32_e32 v10, 0
	v_mov_b32_e32 v11, 0
	v_mov_b32_e32 v12, 0
	v_mov_b32_e32 v13, 0
	v_mov_b32_e32 v14, 0
	v_mov_b32_e32 v15, 0
	v_mov_b32_e32 v16, 0
	v_mov_b32_e32 v17, 0
	v_mov_b32_e32 v18, 0
	v_mov_b32_e32 v19, 0
	v_mov_b32_e32 v20, 0
	v_mov_b32_e32 v21, 0
	v_mov_b32_e32 v22, 0
	v_mov_b32_e32 v23, 0
	v_mov_b32_e32 v24, 0
	v_mov_b32_e32 v25, 0
	v_mov_b32_e32 v26, 0
	v_mov_b32_e32 v27, 0
	v_mov_b32_e32 v28, 0
	v_mov_b32_e32 v29, 0
	v_mov_b32_e32 v30, 0
	v_mov_b32_e32 v31, 0
	v_mov_b32_e32 v32, 0
	v_mov_b32_e32 v33, 0
	v_mov_b32_e32 v34, 0
	v_mov_b32_e32 v35, 0
	v_mov_b32_e32 v36, 0
	v_mov_b32_e32 v37, 0
	v_mov_b32_e32 v38, 0
	v_mov_b32_e32 v39, 0
	v_mov_b32_e32 v40, 0
	v_mov_b32_e32 v41, 0
	v_mov_b32_e32 v42, 0
	v_mov_b32_e32 v43, 0
	v_mov_b32_e32 v44, 0
	v_mov_b32_e32 v45, 0
	v_mov_b32_e32 v46, 0
	v_mov_b32_e32 v47, 0
	v_mov_b32_e32 v48, 0
	v_mov_b32_e32 v49, 0
	v_mov_b32_e32 v50, 0
	v_mov_b32_e32 v51, 0
	v_mov_b32_e32 v52, 0
	v_mov_b32_e32 v53, 0
	v_mov_b32_e32 v54, 0
	v_mov_b32_e32 v55, 0
	v_mov_b32_e32 v56, 0
	v_mov_b32_e32 v57, 0
	v_mov_b32_e32 v58, 0
	v_mov_b32_e32 v59, 0
	v_mov_b32_e32 v60, 0
	v_mov_b32_e32 v61, 0
	v_mov_b32_e32 v62, 0
	v_mov_b32_e32 v63, 0
	v_mov_b32_e32 v178, 0
	v_mov_b32_e32 v179, 0
	v_mov_b32_e32 v206, 0
	v_mov_b32_e32 v207, 0
	s_waitcnt vmcnt(24)
	v_cmp_ne_u32_e32 vcc, 31, v238
	v_lshl_add_u32 v214, v237, 2, s87
	v_mul_f32_e32 v242, 0x3fb8aa3b, v242
	v_mul_f32_e32 v243, 0x3fb8aa3b, v243
	v_mul_f32_e32 v244, 0x3fb8aa3b, v244
	v_mul_f32_e32 v245, 0x3fb8aa3b, v245
	s_nop 0
	v_cndmask_b32_e32 v242, 0, v242, vcc
	v_cndmask_b32_e32 v243, 0, v243, vcc
	v_cndmask_b32_e32 v244, 0, v244, vcc
	v_cndmask_b32_e32 v245, 0, v245, vcc
	ds_write_b32 v214, v242 offset:16384
	ds_write_b32 v214, v243 offset:16640
	ds_write_b32 v214, v244 offset:16896
	ds_write_b32 v214, v245 offset:17152
	s_mov_b32 s24, 0
.Lna_local:
	s_cmp_eq_u32 s24, 7
	s_cbranch_scc1 .Lna_l7
	s_add_u32 s20, s20, 0x48000
	s_addc_u32 s21, s21, 0
	s_add_u32 s22, s22, 0x48000
	s_addc_u32 s23, s23, 0
	s_branch .Lna_l8
.Lna_l7:
	s_mul_i32 s12, s17, 0x1200
	s_add_u32 s20, s18, s12
	s_addc_u32 s21, s19, 0
	s_add_u32 s22, s20, 0x800
	s_addc_u32 s23, s21, 0
	s_add_u32 s20, s20, 0x400
	s_addc_u32 s21, s21, 0
.Lna_l8:
	s_waitcnt vmcnt(8)
	ds_read2_b32 v[64:65], v233 offset0:32 offset1:33
	ds_read2_b32 v[66:67], v233 offset0:34 offset1:35
	ds_read2_b32 v[68:69], v233 offset0:40 offset1:41
	ds_read2_b32 v[70:71], v233 offset0:42 offset1:43
	ds_read2_b32 v[72:73], v233 offset0:48 offset1:49
	ds_read2_b32 v[74:75], v233 offset0:50 offset1:51
	ds_read2_b32 v[76:77], v233 offset0:56 offset1:57
	ds_read2_b32 v[78:79], v233 offset0:58 offset1:59
	ds_read_b128 v[162:165], v228 offset:8192
	ds_read_b128 v[166:169], v229 offset:8192
	ds_read_b128 v[170:173], v230 offset:8192
	ds_read_b128 v[182:185], v231 offset:8192
	s_waitcnt lgkmcnt(3)
	v_mfma_f32_32x32x16_bf16 v[64:79], v[162:165], v[128:131], v[64:79]
	ds_read_b128 v[186:189], v228 offset:12288
	ds_read_b128 v[190:193], v229 offset:12288
	ds_read_b128 v[194:197], v230 offset:12288
	ds_read_b128 v[198:201], v231 offset:12288
	ds_read2_b32 v[108:109], v233 offset0:24 offset1:25
	ds_read2_b32 v[110:111], v233 offset0:26 offset1:27
	ds_read2_b32 v[80:81], v233 offset0:64 offset1:65
	ds_read2_b32 v[82:83], v233 offset0:66 offset1:67
	s_waitcnt lgkmcnt(10)
	v_mfma_f32_32x32x16_bf16 v[64:79], v[166:169], v[132:135], v[64:79]
	s_waitcnt lgkmcnt(9)
	v_mfma_f32_32x32x16_bf16 v[64:79], v[170:173], v[136:139], v[64:79]
	s_waitcnt lgkmcnt(8)
	v_mfma_f32_32x32x16_bf16 v[64:79], v[182:185], v[140:143], v[64:79]
	s_waitcnt lgkmcnt(2)
	v_mfma_f32_32x32x16_bf16 v[96:111], v[162:165], v[144:147], v[96:111]
	ds_read2_b32 v[112:113], v233 offset0:32 offset1:33
	ds_read2_b32 v[114:115], v233 offset0:34 offset1:35
	ds_read2_b32 v[116:117], v233 offset0:40 offset1:41
	ds_read2_b32 v[118:119], v233 offset0:42 offset1:43
	ds_read2_b32 v[120:121], v233 offset0:48 offset1:49
	ds_read2_b32 v[122:123], v233 offset0:50 offset1:51
	ds_read2_b32 v[124:125], v233 offset0:56 offset1:57
	ds_read2_b32 v[126:127], v233 offset0:58 offset1:59
	s_nop 1
	v_exp_f32_e32 v64, v64
	v_exp_f32_e32 v65, v65
	v_exp_f32_e32 v66, v66
	v_exp_f32_e32 v67, v67
	v_exp_f32_e32 v68, v68
	v_mfma_f32_32x32x16_bf16 v[96:111], v[166:169], v[148:151], v[96:111]
	v_exp_f32_e32 v69, v69
	v_exp_f32_e32 v70, v70
	v_exp_f32_e32 v71, v71
	v_exp_f32_e32 v72, v72
	v_exp_f32_e32 v73, v73
	v_mfma_f32_32x32x16_bf16 v[96:111], v[170:173], v[152:155], v[96:111]
	v_exp_f32_e32 v74, v74
	v_exp_f32_e32 v75, v75
	v_exp_f32_e32 v76, v76
	v_exp_f32_e32 v77, v77
	v_exp_f32_e32 v78, v78
	v_mfma_f32_32x32x16_bf16 v[96:111], v[182:185], v[156:159], v[96:111]
	v_exp_f32_e32 v79, v79
	s_mov_b32 s26, 0x1ff
	s_mov_b32 s27, 0x1fff
	v_cndmask_b32_e64 v64, 0, v64, s[26:27]
	s_mov_b32 s26, 0x3ff
	s_mov_b32 s27, 0x3fff
	v_cndmask_b32_e64 v65, 0, v65, s[26:27]
	s_mov_b32 s26, 0x7ff
	s_mov_b32 s27, 0x7fff
	v_cndmask_b32_e64 v66, 0, v66, s[26:27]
	s_mov_b32 s26, 0xfff
	s_mov_b32 s27, 0xffff
	v_cndmask_b32_e64 v67, 0, v67, s[26:27]
	s_waitcnt lgkmcnt(8)
	v_mfma_f32_32x32x16_bf16 v[80:95], v[186:189], v[128:131], v[80:95]
	s_mov_b32 s26, 0x1ffff
	s_mov_b32 s27, 0x1fffff
	v_cndmask_b32_e64 v68, 0, v68, s[26:27]
	s_mov_b32 s26, 0x3ffff
	s_mov_b32 s27, 0x3fffff
	v_cndmask_b32_e64 v69, 0, v69, s[26:27]
	s_mov_b32 s26, 0x7ffff
	s_mov_b32 s27, 0x7fffff
	v_cndmask_b32_e64 v70, 0, v70, s[26:27]
	s_mov_b32 s26, 0xfffff
	s_mov_b32 s27, 0xffffff
	v_cndmask_b32_e64 v71, 0, v71, s[26:27]
	s_mov_b32 s26, 0x1fffe00
	s_mov_b32 s27, 0x1fffe000
	v_cndmask_b32_e64 v72, 0, v72, s[26:27]
	v_mfma_f32_32x32x16_bf16 v[80:95], v[190:193], v[132:135], v[80:95]
	s_mov_b32 s26, 0x3fffc00
	s_mov_b32 s27, 0x3fffc000
	v_cndmask_b32_e64 v73, 0, v73, s[26:27]
	s_mov_b32 s26, 0x7fff800
	s_mov_b32 s27, 0x7fff8000
	v_cndmask_b32_e64 v74, 0, v74, s[26:27]
	s_mov_b32 s26, 0xffff000
	s_mov_b32 s27, 0xffff0000
	v_cndmask_b32_e64 v75, 0, v75, s[26:27]
	s_mov_b32 s26, 0xfffe0000
	s_mov_b32 s27, 0xffe00000
	v_cndmask_b32_e64 v76, 0, v76, s[26:27]
	s_mov_b32 s26, 0xfffc0000
	s_mov_b32 s27, 0xffc00000
	v_cndmask_b32_e64 v77, 0, v77, s[26:27]
	v_mfma_f32_32x32x16_bf16 v[80:95], v[194:197], v[136:139], v[80:95]
	s_mov_b32 s26, 0xfff80000
	s_mov_b32 s27, 0xff800000
	v_cndmask_b32_e64 v78, 0, v78, s[26:27]
	s_mov_b32 s26, 0xfff00000
	s_mov_b32 s27, 0xff000000
	v_cndmask_b32_e64 v79, 0, v79, s[26:27]
	v_add_f32_e32 v178, v64, v178
	v_add_f32_e32 v206, v65, v206
	v_add_f32_e32 v178, v66, v178
	v_mfma_f32_32x32x16_bf16 v[80:95], v[198:201], v[140:143], v[80:95]
	v_add_f32_e32 v206, v67, v206
	v_add_f32_e32 v178, v68, v178
	v_add_f32_e32 v206, v69, v206
	v_add_f32_e32 v178, v70, v178
	v_add_f32_e32 v206, v71, v206
	s_waitcnt lgkmcnt(0)
	v_mfma_f32_32x32x16_bf16 v[112:127], v[186:189], v[144:147], v[112:127]
	s_add_i32 m0, s87, 0x2000
	s_add_u32 s28, s20, 0x0
	s_addc_u32 s29, s21, 0
	global_load_lds_dwordx4 v234, s[28:29]
	s_add_i32 m0, s87, 0x2400
	s_add_u32 s28, s20, 0x9000
	s_addc_u32 s29, s21, 0
	global_load_lds_dwordx4 v235, s[28:29]
	v_add_f32_e32 v178, v72, v178
	v_add_f32_e32 v206, v73, v206
	v_add_f32_e32 v178, v74, v178
	v_add_f32_e32 v206, v75, v206
	v_add_f32_e32 v178, v76, v178
	v_mfma_f32_32x32x16_bf16 v[112:127], v[190:193], v[148:151], v[112:127]
	s_add_i32 m0, s87, 0x2800
	s_add_u32 s28, s20, 0x12000
	s_addc_u32 s29, s21, 0
	global_load_lds_dwordx4 v234, s[28:29]
	s_add_i32 m0, s87, 0x2c00
	s_add_u32 s28, s20, 0x1b000
	s_addc_u32 s29, s21, 0
	global_load_lds_dwordx4 v235, s[28:29]
	v_add_f32_e32 v206, v77, v206
	v_add_f32_e32 v178, v78, v178
	v_add_f32_e32 v206, v79, v206
	v_cvt_pk_bf16_f32 v64, v64, v65
	v_cvt_pk_bf16_f32 v65, v66, v67
	v_mfma_f32_32x32x16_bf16 v[112:127], v[194:197], v[152:155], v[112:127]
	s_add_i32 m0, s87, 0x3000
	s_add_u32 s28, s20, 0x24000
	s_addc_u32 s29, s21, 0
	global_load_lds_dwordx4 v234, s[28:29]
	s_add_i32 m0, s87, 0x3400
	s_add_u32 s28, s20, 0x2d000
	s_addc_u32 s29, s21, 0
	global_load_lds_dwordx4 v235, s[28:29]
	v_cvt_pk_bf16_f32 v66, v68, v69
	v_cvt_pk_bf16_f32 v67, v70, v71
	v_cvt_pk_bf16_f32 v68, v72, v73
	v_cvt_pk_bf16_f32 v69, v74, v75
	v_cvt_pk_bf16_f32 v70, v76, v77
	v_mfma_f32_32x32x16_bf16 v[112:127], v[198:201], v[156:159], v[112:127]
	s_add_i32 m0, s87, 0x3800
	s_add_u32 s28, s20, 0x36000
	s_addc_u32 s29, s21, 0
	global_load_lds_dwordx4 v234, s[28:29]
	s_add_i32 m0, s87, 0x3c00
	s_add_u32 s28, s20, 0x3f000
	s_addc_u32 s29, s21, 0
	global_load_lds_dwordx4 v235, s[28:29]
	v_cvt_pk_bf16_f32 v71, v78, v79
	v_exp_f32_e32 v108, v108
	v_exp_f32_e32 v109, v109
	v_exp_f32_e32 v110, v110
	v_exp_f32_e32 v111, v111
	s_waitcnt vmcnt(8)
	ds_read_b64_tr_b16 v[202:203], v232
	ds_read_b64_tr_b16 v[204:205], v232 offset:1024
	ds_read_b64_tr_b16 v[210:211], v232 offset:512
	ds_read_b64_tr_b16 v[212:213], v232 offset:1536
	ds_read_b64_tr_b16 v[220:221], v232 offset:2048
	ds_read_b64_tr_b16 v[222:223], v232 offset:3072
	s_mov_b32 s26, 0x1
	s_mov_b32 s27, 0x1f
	v_cndmask_b32_e64 v108, 0, v108, s[26:27]
	s_mov_b32 s26, 0x3
	s_mov_b32 s27, 0x3f
	v_cndmask_b32_e64 v109, 0, v109, s[26:27]
	s_mov_b32 s26, 0x7
	s_mov_b32 s27, 0x7f
	v_cndmask_b32_e64 v110, 0, v110, s[26:27]
	s_mov_b32 s26, 0xf
	s_mov_b32 s27, 0xff
	v_cndmask_b32_e64 v111, 0, v111, s[26:27]
	v_add_f32_e32 v179, v108, v179
	v_add_f32_e32 v207, v109, v207
	s_waitcnt lgkmcnt(4)
	v_mfma_f32_32x32x16_bf16 v[48:63], v[202:205], v[64:67], v[48:63]
	ds_read_b64_tr_b16 v[224:225], v232 offset:2560
	ds_read_b64_tr_b16 v[226:227], v232 offset:3584
	v_add_f32_e32 v179, v110, v179
	v_add_f32_e32 v207, v111, v207
	v_mov_b32_e32 v100, 0
	v_mov_b32_e32 v101, 0
	v_cvt_pk_bf16_f32 v102, v108, v109
	v_cvt_pk_bf16_f32 v103, v110, v111
	v_exp_f32_e32 v80, v80
	v_exp_f32_e32 v81, v81
	s_waitcnt lgkmcnt(4)
	v_mfma_f32_32x32x16_bf16 v[32:47], v[210:213], v[64:67], v[32:47]
	ds_read_b64_tr_b16 v[202:203], v232 offset:4096
	ds_read_b64_tr_b16 v[204:205], v232 offset:5120
	v_exp_f32_e32 v82, v82
	v_exp_f32_e32 v83, v83
	s_mov_b32 s26, 0xfe000000
	s_mov_b32 s27, 0xe0000000
	v_cndmask_b32_e64 v80, 0, v80, s[26:27]
	s_mov_b32 s26, 0xfc000000
	s_mov_b32 s27, 0xc0000000
	v_cndmask_b32_e64 v81, 0, v81, s[26:27]
	s_mov_b32 s26, 0xf8000000
	s_mov_b32 s27, 0x80000000
	v_cndmask_b32_e64 v82, 0, v82, s[26:27]
	s_mov_b32 s26, 0xf0000000
	s_mov_b32 s27, 0x0
	v_cndmask_b32_e64 v83, 0, v83, s[26:27]
	v_add_f32_e32 v178, v80, v178
	v_add_f32_e32 v206, v81, v206
	s_waitcnt lgkmcnt(4)
	v_mfma_f32_32x32x16_bf16 v[48:63], v[220:223], v[68:71], v[48:63]
	v_add_f32_e32 v178, v82, v178
	v_add_f32_e32 v206, v83, v206
	v_cvt_pk_bf16_f32 v80, v80, v81
	v_cvt_pk_bf16_f32 v81, v82, v83
	v_mov_b32_e32 v82, 0
	v_mov_b32_e32 v83, 0
	v_exp_f32_e32 v112, v112
	v_exp_f32_e32 v113, v113
	v_mfma_f32_32x32x16_bf16 v[16:31], v[220:223], v[100:103], v[16:31]
	ds_read_b64_tr_b16 v[210:211], v232 offset:4608
	ds_read_b64_tr_b16 v[212:213], v232 offset:5632
	v_exp_f32_e32 v114, v114
	v_exp_f32_e32 v115, v115
	v_exp_f32_e32 v116, v116
	v_exp_f32_e32 v117, v117
	v_exp_f32_e32 v118, v118
	v_exp_f32_e32 v119, v119
	v_exp_f32_e32 v120, v120
	v_exp_f32_e32 v121, v121
	s_waitcnt lgkmcnt(4)
	v_mfma_f32_32x32x16_bf16 v[32:47], v[224:227], v[68:71], v[32:47]
	v_exp_f32_e32 v122, v122
	v_exp_f32_e32 v123, v123
	v_exp_f32_e32 v124, v124
	v_exp_f32_e32 v125, v125
	v_exp_f32_e32 v126, v126
	v_exp_f32_e32 v127, v127
	s_mov_b32 s26, 0x1ff
	s_mov_b32 s27, 0x1fff
	v_cndmask_b32_e64 v112, 0, v112, s[26:27]
	s_mov_b32 s26, 0x3ff
	s_mov_b32 s27, 0x3fff
	v_cndmask_b32_e64 v113, 0, v113, s[26:27]
	v_mfma_f32_32x32x16_bf16 v[0:15], v[224:227], v[100:103], v[0:15]
	ds_read_b64_tr_b16 v[220:221], v232 offset:6144
	ds_read_b64_tr_b16 v[222:223], v232 offset:7168
	s_mov_b32 s26, 0x7ff
	s_mov_b32 s27, 0x7fff
	v_cndmask_b32_e64 v114, 0, v114, s[26:27]
	s_mov_b32 s26, 0xfff
	s_mov_b32 s27, 0xffff
	v_cndmask_b32_e64 v115, 0, v115, s[26:27]
	s_mov_b32 s26, 0x1fffe
	s_mov_b32 s27, 0x1fffe0
	v_cndmask_b32_e64 v116, 0, v116, s[26:27]
	s_mov_b32 s26, 0x3fffc
	s_mov_b32 s27, 0x3fffc0
	v_cndmask_b32_e64 v117, 0, v117, s[26:27]
	s_mov_b32 s26, 0x7fff8
	s_mov_b32 s27, 0x7fff80
	v_cndmask_b32_e64 v118, 0, v118, s[26:27]
	s_mov_b32 s26, 0xffff0
	s_mov_b32 s27, 0xffff00
	v_cndmask_b32_e64 v119, 0, v119, s[26:27]
	s_mov_b32 s26, 0xfffffe00
	s_mov_b32 s27, 0xffffe000
	v_cndmask_b32_e64 v120, 0, v120, s[26:27]
	s_mov_b32 s26, 0xfffffc00
	s_mov_b32 s27, 0xffffc000
	v_cndmask_b32_e64 v121, 0, v121, s[26:27]
	s_waitcnt lgkmcnt(4)
	v_mfma_f32_32x32x16_bf16 v[48:63], v[202:205], v[80:83], v[48:63]
	s_mov_b32 s26, 0xfffff800
	s_mov_b32 s27, 0xffff8000
	v_cndmask_b32_e64 v122, 0, v122, s[26:27]
	s_mov_b32 s26, 0xfffff000
	s_mov_b32 s27, 0xffff0000
	v_cndmask_b32_e64 v123, 0, v123, s[26:27]
	s_mov_b32 s26, 0xfffe0000
	s_mov_b32 s27, 0xffe00000
	v_cndmask_b32_e64 v124, 0, v124, s[26:27]
	s_mov_b32 s26, 0xfffc0000
	s_mov_b32 s27, 0xffc00000
	v_cndmask_b32_e64 v125, 0, v125, s[26:27]
	s_mov_b32 s26, 0xfff80000
	s_mov_b32 s27, 0xff800000
	v_cndmask_b32_e64 v126, 0, v126, s[26:27]
	s_mov_b32 s26, 0xfff00000
	s_mov_b32 s27, 0xff000000
	v_cndmask_b32_e64 v127, 0, v127, s[26:27]
	v_add_f32_e32 v179, v112, v179
	v_add_f32_e32 v207, v113, v207
	v_add_f32_e32 v179, v114, v179
	v_add_f32_e32 v207, v115, v207
	v_add_f32_e32 v179, v116, v179
	v_add_f32_e32 v207, v117, v207
	v_add_f32_e32 v179, v118, v179
	v_add_f32_e32 v207, v119, v207
	v_add_f32_e32 v179, v120, v179
	v_add_f32_e32 v207, v121, v207
	v_add_f32_e32 v179, v122, v179
	v_add_f32_e32 v207, v123, v207
	v_add_f32_e32 v179, v124, v179
	v_add_f32_e32 v207, v125, v207
	v_add_f32_e32 v179, v126, v179
	v_add_f32_e32 v207, v127, v207
	v_cvt_pk_bf16_f32 v112, v112, v113
	v_cvt_pk_bf16_f32 v113, v114, v115
	v_cvt_pk_bf16_f32 v114, v116, v117
	v_cvt_pk_bf16_f32 v115, v118, v119
	v_cvt_pk_bf16_f32 v116, v120, v121
	v_cvt_pk_bf16_f32 v117, v122, v123
	v_cvt_pk_bf16_f32 v118, v124, v125
	v_cvt_pk_bf16_f32 v119, v126, v127
	v_mfma_f32_32x32x16_bf16 v[16:31], v[202:205], v[112:115], v[16:31]
	ds_read_b64_tr_b16 v[224:225], v232 offset:6656
	ds_read_b64_tr_b16 v[226:227], v232 offset:7680
	s_waitcnt lgkmcnt(4)
	v_mfma_f32_32x32x16_bf16 v[32:47], v[210:213], v[80:83], v[32:47]
	v_mfma_f32_32x32x16_bf16 v[0:15], v[210:213], v[112:115], v[0:15]
	s_waitcnt lgkmcnt(2)
	v_mfma_f32_32x32x16_bf16 v[16:31], v[220:223], v[116:119], v[16:31]
	s_waitcnt lgkmcnt(0)
	v_mfma_f32_32x32x16_bf16 v[0:15], v[224:227], v[116:119], v[0:15]
	s_waitcnt lgkmcnt(0)
	s_add_i32 m0, s87, 0x0
	s_add_u32 s28, s22, 0x0
	s_addc_u32 s29, s23, 0
	global_load_lds_dwordx4 v236, s[28:29]
	s_add_i32 m0, s87, 0x400
	s_add_u32 s28, s22, 0x9000
	s_addc_u32 s29, s23, 0
	global_load_lds_dwordx4 v236, s[28:29]
	s_add_i32 m0, s87, 0x800
	s_add_u32 s28, s22, 0x12000
	s_addc_u32 s29, s23, 0
	global_load_lds_dwordx4 v236, s[28:29]
	s_add_i32 m0, s87, 0xc00
	s_add_u32 s28, s22, 0x1b000
	s_addc_u32 s29, s23, 0
	global_load_lds_dwordx4 v236, s[28:29]
	s_add_i32 m0, s87, 0x1000
	s_add_u32 s28, s22, 0x24000
	s_addc_u32 s29, s23, 0
	global_load_lds_dwordx4 v236, s[28:29]
	s_add_i32 m0, s87, 0x1400
	s_add_u32 s28, s22, 0x2d000
	s_addc_u32 s29, s23, 0
	global_load_lds_dwordx4 v236, s[28:29]
	s_add_i32 m0, s87, 0x1800
	s_add_u32 s28, s22, 0x36000
	s_addc_u32 s29, s23, 0
	global_load_lds_dwordx4 v236, s[28:29]
	s_add_i32 m0, s87, 0x1c00
	s_add_u32 s28, s22, 0x3f000
	s_addc_u32 s29, s23, 0
	global_load_lds_dwordx4 v236, s[28:29]
	v_add_u32_e32 v233, 0x80, v233
	s_add_i32 s24, s24, 1
	s_cmp_lt_u32 s24, 8
	s_cbranch_scc1 .Lna_local
	s_mov_b32 s24, 0
.Lna_ctx:
	s_add_u32 s20, s20, 0x48000
	s_addc_u32 s21, s21, 0
	s_add_u32 s22, s22, 0x48000
	s_addc_u32 s23, s23, 0
	s_waitcnt vmcnt(8)
	ds_read_b128 v[162:165], v228 offset:8192
	ds_read_b128 v[166:169], v229 offset:8192
	ds_read_b128 v[170:173], v230 offset:8192
	ds_read_b128 v[182:185], v231 offset:8192
	s_waitcnt lgkmcnt(3)
	v_mfma_f32_32x32x16_bf16 v[64:79], v[162:165], v[128:131], 0
	ds_read_b128 v[186:189], v228 offset:12288
	ds_read_b128 v[190:193], v229 offset:12288
	ds_read_b128 v[194:197], v230 offset:12288
	ds_read_b128 v[198:201], v231 offset:12288
	s_waitcnt lgkmcnt(6)
	v_mfma_f32_32x32x16_bf16 v[64:79], v[166:169], v[132:135], v[64:79]
	s_waitcnt lgkmcnt(5)
	v_mfma_f32_32x32x16_bf16 v[64:79], v[170:173], v[136:139], v[64:79]
	s_waitcnt lgkmcnt(4)
	v_mfma_f32_32x32x16_bf16 v[64:79], v[182:185], v[140:143], v[64:79]
	v_mfma_f32_32x32x16_bf16 v[96:111], v[162:165], v[144:147], 0
	s_nop 7
	s_nop 2
	v_exp_f32_e32 v64, v64
	v_exp_f32_e32 v65, v65
	v_exp_f32_e32 v66, v66
	v_exp_f32_e32 v67, v67
	v_exp_f32_e32 v68, v68
	v_mfma_f32_32x32x16_bf16 v[96:111], v[166:169], v[148:151], v[96:111]
	v_exp_f32_e32 v69, v69
	v_exp_f32_e32 v70, v70
	v_exp_f32_e32 v71, v71
	v_exp_f32_e32 v72, v72
	v_exp_f32_e32 v73, v73
	v_mfma_f32_32x32x16_bf16 v[96:111], v[170:173], v[152:155], v[96:111]
	v_exp_f32_e32 v74, v74
	v_exp_f32_e32 v75, v75
	v_exp_f32_e32 v76, v76
	v_exp_f32_e32 v77, v77
	v_exp_f32_e32 v78, v78
	v_mfma_f32_32x32x16_bf16 v[96:111], v[182:185], v[156:159], v[96:111]
	v_exp_f32_e32 v79, v79
	v_add_f32_e32 v178, v64, v178
	v_add_f32_e32 v206, v65, v206
	v_add_f32_e32 v178, v66, v178
	v_add_f32_e32 v206, v67, v206
	s_waitcnt lgkmcnt(3)
	v_mfma_f32_32x32x16_bf16 v[80:95], v[186:189], v[128:131], 0
	v_add_f32_e32 v178, v68, v178
	v_add_f32_e32 v206, v69, v206
	v_add_f32_e32 v178, v70, v178
	v_add_f32_e32 v206, v71, v206
	v_add_f32_e32 v178, v72, v178
	s_waitcnt lgkmcnt(2)
	v_mfma_f32_32x32x16_bf16 v[80:95], v[190:193], v[132:135], v[80:95]
	v_add_f32_e32 v206, v73, v206
	v_add_f32_e32 v178, v74, v178
	v_add_f32_e32 v206, v75, v206
	v_add_f32_e32 v178, v76, v178
	v_add_f32_e32 v206, v77, v206
	s_waitcnt lgkmcnt(1)
	v_mfma_f32_32x32x16_bf16 v[80:95], v[194:197], v[136:139], v[80:95]
	v_add_f32_e32 v178, v78, v178
	v_add_f32_e32 v206, v79, v206
	v_cvt_pk_bf16_f32 v64, v64, v65
	v_cvt_pk_bf16_f32 v65, v66, v67
	v_cvt_pk_bf16_f32 v66, v68, v69
	s_waitcnt lgkmcnt(0)
	v_mfma_f32_32x32x16_bf16 v[80:95], v[198:201], v[140:143], v[80:95]
	v_cvt_pk_bf16_f32 v67, v70, v71
	v_cvt_pk_bf16_f32 v68, v72, v73
	v_cvt_pk_bf16_f32 v69, v74, v75
	v_cvt_pk_bf16_f32 v70, v76, v77
	v_cvt_pk_bf16_f32 v71, v78, v79
	v_mfma_f32_32x32x16_bf16 v[112:127], v[186:189], v[144:147], 0
	s_add_i32 m0, s87, 0x2000
	s_add_u32 s28, s20, 0x0
	s_addc_u32 s29, s21, 0
	global_load_lds_dwordx4 v234, s[28:29]
	s_add_i32 m0, s87, 0x2400
	s_add_u32 s28, s20, 0x9000
	s_addc_u32 s29, s21, 0
	global_load_lds_dwordx4 v235, s[28:29]
	v_exp_f32_e32 v96, v96
	v_exp_f32_e32 v97, v97
	v_exp_f32_e32 v98, v98
	v_exp_f32_e32 v99, v99
	v_exp_f32_e32 v100, v100
	v_mfma_f32_32x32x16_bf16 v[112:127], v[190:193], v[148:151], v[112:127]
	s_add_i32 m0, s87, 0x2800
	s_add_u32 s28, s20, 0x12000
	s_addc_u32 s29, s21, 0
	global_load_lds_dwordx4 v234, s[28:29]
	s_add_i32 m0, s87, 0x2c00
	s_add_u32 s28, s20, 0x1b000
	s_addc_u32 s29, s21, 0
	global_load_lds_dwordx4 v235, s[28:29]
	v_exp_f32_e32 v101, v101
	v_exp_f32_e32 v102, v102
	v_exp_f32_e32 v103, v103
	v_exp_f32_e32 v104, v104
	v_exp_f32_e32 v105, v105
	v_mfma_f32_32x32x16_bf16 v[112:127], v[194:197], v[152:155], v[112:127]
	s_add_i32 m0, s87, 0x3000
	s_add_u32 s28, s20, 0x24000
	s_addc_u32 s29, s21, 0
	global_load_lds_dwordx4 v234, s[28:29]
	s_add_i32 m0, s87, 0x3400
	s_add_u32 s28, s20, 0x2d000
	s_addc_u32 s29, s21, 0
	global_load_lds_dwordx4 v235, s[28:29]
	v_exp_f32_e32 v106, v106
	v_exp_f32_e32 v107, v107
	v_exp_f32_e32 v108, v108
	v_exp_f32_e32 v109, v109
	v_exp_f32_e32 v110, v110
	v_mfma_f32_32x32x16_bf16 v[112:127], v[198:201], v[156:159], v[112:127]
	s_add_i32 m0, s87, 0x3800
	s_add_u32 s28, s20, 0x36000
	s_addc_u32 s29, s21, 0
	global_load_lds_dwordx4 v234, s[28:29]
	s_add_i32 m0, s87, 0x3c00
	s_add_u32 s28, s20, 0x3f000
	s_addc_u32 s29, s21, 0
	global_load_lds_dwordx4 v235, s[28:29]
	v_exp_f32_e32 v111, v111
	v_add_f32_e32 v179, v96, v179
	v_add_f32_e32 v207, v97, v207
	v_add_f32_e32 v179, v98, v179
	v_add_f32_e32 v207, v99, v207
	s_waitcnt vmcnt(8)
	ds_read_b64_tr_b16 v[202:203], v232
	ds_read_b64_tr_b16 v[204:205], v232 offset:1024
	ds_read_b64_tr_b16 v[210:211], v232 offset:512
	ds_read_b64_tr_b16 v[212:213], v232 offset:1536
	ds_read_b64_tr_b16 v[220:221], v232 offset:2048
	ds_read_b64_tr_b16 v[222:223], v232 offset:3072
	v_add_f32_e32 v179, v100, v179
	v_add_f32_e32 v207, v101, v207
	v_add_f32_e32 v179, v102, v179
	v_add_f32_e32 v207, v103, v207
	v_add_f32_e32 v179, v104, v179
	v_add_f32_e32 v207, v105, v207
	s_waitcnt lgkmcnt(4)
	v_mfma_f32_32x32x16_bf16 v[48:63], v[202:205], v[64:67], v[48:63]
	v_add_f32_e32 v179, v106, v179
	v_add_f32_e32 v207, v107, v207
	v_add_f32_e32 v179, v108, v179
	v_add_f32_e32 v207, v109, v207
	v_add_f32_e32 v179, v110, v179
	v_add_f32_e32 v207, v111, v207
	v_cvt_pk_bf16_f32 v96, v96, v97
	v_cvt_pk_bf16_f32 v97, v98, v99
	v_cvt_pk_bf16_f32 v98, v100, v101
	v_cvt_pk_bf16_f32 v99, v102, v103
	v_cvt_pk_bf16_f32 v100, v104, v105
	v_cvt_pk_bf16_f32 v101, v106, v107
	v_cvt_pk_bf16_f32 v102, v108, v109
	v_cvt_pk_bf16_f32 v103, v110, v111
	v_mfma_f32_32x32x16_bf16 v[16:31], v[202:205], v[96:99], v[16:31]
	ds_read_b64_tr_b16 v[224:225], v232 offset:2560
	ds_read_b64_tr_b16 v[226:227], v232 offset:3584
	v_exp_f32_e32 v80, v80
	v_exp_f32_e32 v81, v81
	v_exp_f32_e32 v82, v82
	v_exp_f32_e32 v83, v83
	v_exp_f32_e32 v84, v84
	v_exp_f32_e32 v85, v85
	v_exp_f32_e32 v86, v86
	v_exp_f32_e32 v87, v87
	s_waitcnt lgkmcnt(4)
	v_mfma_f32_32x32x16_bf16 v[32:47], v[210:213], v[64:67], v[32:47]
	v_exp_f32_e32 v88, v88
	v_exp_f32_e32 v89, v89
	v_exp_f32_e32 v90, v90
	v_exp_f32_e32 v91, v91
	v_exp_f32_e32 v92, v92
	v_exp_f32_e32 v93, v93
	v_exp_f32_e32 v94, v94
	v_exp_f32_e32 v95, v95
	v_mfma_f32_32x32x16_bf16 v[0:15], v[210:213], v[96:99], v[0:15]
	ds_read_b64_tr_b16 v[202:203], v232 offset:4096
	ds_read_b64_tr_b16 v[204:205], v232 offset:5120
	v_add_f32_e32 v178, v80, v178
	v_add_f32_e32 v206, v81, v206
	v_add_f32_e32 v178, v82, v178
	v_add_f32_e32 v206, v83, v206
	v_add_f32_e32 v178, v84, v178
	v_add_f32_e32 v206, v85, v206
	v_add_f32_e32 v178, v86, v178
	v_add_f32_e32 v206, v87, v206
	s_waitcnt lgkmcnt(4)
	v_mfma_f32_32x32x16_bf16 v[48:63], v[220:223], v[68:71], v[48:63]
	v_add_f32_e32 v178, v88, v178
	v_add_f32_e32 v206, v89, v206
	v_add_f32_e32 v178, v90, v178
	v_add_f32_e32 v206, v91, v206
	v_add_f32_e32 v178, v92, v178
	v_add_f32_e32 v206, v93, v206
	v_add_f32_e32 v178, v94, v178
	v_add_f32_e32 v206, v95, v206
	v_mfma_f32_32x32x16_bf16 v[16:31], v[220:223], v[100:103], v[16:31]
	ds_read_b64_tr_b16 v[210:211], v232 offset:4608
	ds_read_b64_tr_b16 v[212:213], v232 offset:5632
	v_cvt_pk_bf16_f32 v80, v80, v81
	v_cvt_pk_bf16_f32 v81, v82, v83
	v_cvt_pk_bf16_f32 v82, v84, v85
	v_cvt_pk_bf16_f32 v83, v86, v87
	v_cvt_pk_bf16_f32 v84, v88, v89
	v_cvt_pk_bf16_f32 v85, v90, v91
	v_cvt_pk_bf16_f32 v86, v92, v93
	v_cvt_pk_bf16_f32 v87, v94, v95
	s_waitcnt lgkmcnt(4)
	v_mfma_f32_32x32x16_bf16 v[32:47], v[224:227], v[68:71], v[32:47]
	v_exp_f32_e32 v112, v112
	v_exp_f32_e32 v113, v113
	v_exp_f32_e32 v114, v114
	v_exp_f32_e32 v115, v115
	v_exp_f32_e32 v116, v116
	v_exp_f32_e32 v117, v117
	v_exp_f32_e32 v118, v118
	v_exp_f32_e32 v119, v119
	v_mfma_f32_32x32x16_bf16 v[0:15], v[224:227], v[100:103], v[0:15]
	ds_read_b64_tr_b16 v[220:221], v232 offset:6144
	ds_read_b64_tr_b16 v[222:223], v232 offset:7168
	v_exp_f32_e32 v120, v120
	v_exp_f32_e32 v121, v121
	v_exp_f32_e32 v122, v122
	v_exp_f32_e32 v123, v123
	v_exp_f32_e32 v124, v124
	v_exp_f32_e32 v125, v125
	v_exp_f32_e32 v126, v126
	v_exp_f32_e32 v127, v127
	s_waitcnt lgkmcnt(4)
	v_mfma_f32_32x32x16_bf16 v[48:63], v[202:205], v[80:83], v[48:63]
	v_add_f32_e32 v179, v112, v179
	v_add_f32_e32 v207, v113, v207
	v_add_f32_e32 v179, v114, v179
	v_add_f32_e32 v207, v115, v207
	v_add_f32_e32 v179, v116, v179
	v_add_f32_e32 v207, v117, v207
	v_add_f32_e32 v179, v118, v179
	v_add_f32_e32 v207, v119, v207
	v_add_f32_e32 v179, v120, v179
	v_add_f32_e32 v207, v121, v207
	v_add_f32_e32 v179, v122, v179
	v_add_f32_e32 v207, v123, v207
	v_add_f32_e32 v179, v124, v179
	v_add_f32_e32 v207, v125, v207
	v_add_f32_e32 v179, v126, v179
	v_add_f32_e32 v207, v127, v207
	v_cvt_pk_bf16_f32 v112, v112, v113
	v_cvt_pk_bf16_f32 v113, v114, v115
	v_cvt_pk_bf16_f32 v114, v116, v117
	v_cvt_pk_bf16_f32 v115, v118, v119
	v_cvt_pk_bf16_f32 v116, v120, v121
	v_cvt_pk_bf16_f32 v117, v122, v123
	v_cvt_pk_bf16_f32 v118, v124, v125
	v_cvt_pk_bf16_f32 v119, v126, v127
	v_mfma_f32_32x32x16_bf16 v[16:31], v[202:205], v[112:115], v[16:31]
	ds_read_b64_tr_b16 v[224:225], v232 offset:6656
	ds_read_b64_tr_b16 v[226:227], v232 offset:7680
	s_waitcnt lgkmcnt(4)
	v_mfma_f32_32x32x16_bf16 v[32:47], v[210:213], v[80:83], v[32:47]
	v_mfma_f32_32x32x16_bf16 v[0:15], v[210:213], v[112:115], v[0:15]
	s_waitcnt lgkmcnt(2)
	v_mfma_f32_32x32x16_bf16 v[48:63], v[220:223], v[84:87], v[48:63]
	v_mfma_f32_32x32x16_bf16 v[16:31], v[220:223], v[116:119], v[16:31]
	s_waitcnt lgkmcnt(0)
	v_mfma_f32_32x32x16_bf16 v[32:47], v[224:227], v[84:87], v[32:47]
	v_mfma_f32_32x32x16_bf16 v[0:15], v[224:227], v[116:119], v[0:15]
	s_waitcnt lgkmcnt(0)
	s_add_i32 m0, s87, 0x0
	s_add_u32 s28, s22, 0x0
	s_addc_u32 s29, s23, 0
	global_load_lds_dwordx4 v236, s[28:29]
	s_add_i32 m0, s87, 0x400
	s_add_u32 s28, s22, 0x9000
	s_addc_u32 s29, s23, 0
	global_load_lds_dwordx4 v236, s[28:29]
	s_add_i32 m0, s87, 0x800
	s_add_u32 s28, s22, 0x12000
	s_addc_u32 s29, s23, 0
	global_load_lds_dwordx4 v236, s[28:29]
	s_add_i32 m0, s87, 0xc00
	s_add_u32 s28, s22, 0x1b000
	s_addc_u32 s29, s23, 0
	global_load_lds_dwordx4 v236, s[28:29]
	s_add_i32 m0, s87, 0x1000
	s_add_u32 s28, s22, 0x24000
	s_addc_u32 s29, s23, 0
	global_load_lds_dwordx4 v236, s[28:29]
	s_add_i32 m0, s87, 0x1400
	s_add_u32 s28, s22, 0x2d000
	s_addc_u32 s29, s23, 0
	global_load_lds_dwordx4 v236, s[28:29]
	s_add_i32 m0, s87, 0x1800
	s_add_u32 s28, s22, 0x36000
	s_addc_u32 s29, s23, 0
	global_load_lds_dwordx4 v236, s[28:29]
	s_add_i32 m0, s87, 0x1c00
	s_add_u32 s28, s22, 0x3f000
	s_addc_u32 s29, s23, 0
	global_load_lds_dwordx4 v236, s[28:29]
	s_add_i32 s24, s24, 1
	s_cmp_lt_u32 s24, 3
	s_cbranch_scc1 .Lna_ctx
	s_waitcnt vmcnt(8)
	ds_read_b128 v[162:165], v228 offset:8192
	ds_read_b128 v[166:169], v229 offset:8192
	ds_read_b128 v[170:173], v230 offset:8192
	ds_read_b128 v[182:185], v231 offset:8192
	s_waitcnt lgkmcnt(3)
	v_mfma_f32_32x32x16_bf16 v[64:79], v[162:165], v[128:131], 0
	ds_read_b128 v[186:189], v228 offset:12288
	ds_read_b128 v[190:193], v229 offset:12288
	ds_read_b128 v[194:197], v230 offset:12288
	ds_read_b128 v[198:201], v231 offset:12288
	s_waitcnt lgkmcnt(6)
	v_mfma_f32_32x32x16_bf16 v[64:79], v[166:169], v[132:135], v[64:79]
	s_waitcnt lgkmcnt(5)
	v_mfma_f32_32x32x16_bf16 v[64:79], v[170:173], v[136:139], v[64:79]
	s_waitcnt lgkmcnt(4)
	v_mfma_f32_32x32x16_bf16 v[64:79], v[182:185], v[140:143], v[64:79]
	v_mfma_f32_32x32x16_bf16 v[96:111], v[162:165], v[144:147], 0
	s_nop 7
	s_nop 2
	v_exp_f32_e32 v64, v64
	v_exp_f32_e32 v65, v65
	v_exp_f32_e32 v66, v66
	v_exp_f32_e32 v67, v67
	v_exp_f32_e32 v68, v68
	v_mfma_f32_32x32x16_bf16 v[96:111], v[166:169], v[148:151], v[96:111]
	v_exp_f32_e32 v69, v69
	v_exp_f32_e32 v70, v70
	v_exp_f32_e32 v71, v71
	v_exp_f32_e32 v72, v72
	v_exp_f32_e32 v73, v73
	v_mfma_f32_32x32x16_bf16 v[96:111], v[170:173], v[152:155], v[96:111]
	v_exp_f32_e32 v74, v74
	v_exp_f32_e32 v75, v75
	v_exp_f32_e32 v76, v76
	v_exp_f32_e32 v77, v77
	v_exp_f32_e32 v78, v78
	v_mfma_f32_32x32x16_bf16 v[96:111], v[182:185], v[156:159], v[96:111]
	v_exp_f32_e32 v79, v79
	v_add_f32_e32 v178, v64, v178
	v_add_f32_e32 v206, v65, v206
	v_add_f32_e32 v178, v66, v178
	v_add_f32_e32 v206, v67, v206
	s_waitcnt lgkmcnt(3)
	v_mfma_f32_32x32x16_bf16 v[80:95], v[186:189], v[128:131], 0
	v_add_f32_e32 v178, v68, v178
	v_add_f32_e32 v206, v69, v206
	v_add_f32_e32 v178, v70, v178
	v_add_f32_e32 v206, v71, v206
	v_add_f32_e32 v178, v72, v178
	s_waitcnt lgkmcnt(2)
	v_mfma_f32_32x32x16_bf16 v[80:95], v[190:193], v[132:135], v[80:95]
	v_add_f32_e32 v206, v73, v206
	v_add_f32_e32 v178, v74, v178
	v_add_f32_e32 v206, v75, v206
	v_add_f32_e32 v178, v76, v178
	v_add_f32_e32 v206, v77, v206
	s_waitcnt lgkmcnt(1)
	v_mfma_f32_32x32x16_bf16 v[80:95], v[194:197], v[136:139], v[80:95]
	v_add_f32_e32 v178, v78, v178
	v_add_f32_e32 v206, v79, v206
	v_cvt_pk_bf16_f32 v64, v64, v65
	v_cvt_pk_bf16_f32 v65, v66, v67
	v_cvt_pk_bf16_f32 v66, v68, v69
	s_waitcnt lgkmcnt(0)
	v_mfma_f32_32x32x16_bf16 v[80:95], v[198:201], v[140:143], v[80:95]
	v_cvt_pk_bf16_f32 v67, v70, v71
	v_cvt_pk_bf16_f32 v68, v72, v73
	v_cvt_pk_bf16_f32 v69, v74, v75
	v_cvt_pk_bf16_f32 v70, v76, v77
	v_cvt_pk_bf16_f32 v71, v78, v79
	v_mfma_f32_32x32x16_bf16 v[112:127], v[186:189], v[144:147], 0
	v_exp_f32_e32 v96, v96
	v_exp_f32_e32 v97, v97
	v_exp_f32_e32 v98, v98
	v_exp_f32_e32 v99, v99
	v_exp_f32_e32 v100, v100
	v_mfma_f32_32x32x16_bf16 v[112:127], v[190:193], v[148:151], v[112:127]
	v_exp_f32_e32 v101, v101
	v_exp_f32_e32 v102, v102
	v_exp_f32_e32 v103, v103
	v_exp_f32_e32 v104, v104
	v_exp_f32_e32 v105, v105
	v_mfma_f32_32x32x16_bf16 v[112:127], v[194:197], v[152:155], v[112:127]
	v_exp_f32_e32 v106, v106
	v_exp_f32_e32 v107, v107
	v_exp_f32_e32 v108, v108
	v_exp_f32_e32 v109, v109
	v_exp_f32_e32 v110, v110
	v_mfma_f32_32x32x16_bf16 v[112:127], v[198:201], v[156:159], v[112:127]
	v_exp_f32_e32 v111, v111
	v_add_f32_e32 v179, v96, v179
	v_add_f32_e32 v207, v97, v207
	v_add_f32_e32 v179, v98, v179
	v_add_f32_e32 v207, v99, v207
	s_waitcnt vmcnt(0)
	ds_read_b64_tr_b16 v[202:203], v232
	ds_read_b64_tr_b16 v[204:205], v232 offset:1024
	ds_read_b64_tr_b16 v[210:211], v232 offset:512
	ds_read_b64_tr_b16 v[212:213], v232 offset:1536
	ds_read_b64_tr_b16 v[220:221], v232 offset:2048
	ds_read_b64_tr_b16 v[222:223], v232 offset:3072
	v_add_f32_e32 v179, v100, v179
	v_add_f32_e32 v207, v101, v207
	v_add_f32_e32 v179, v102, v179
	v_add_f32_e32 v207, v103, v207
	v_add_f32_e32 v179, v104, v179
	v_add_f32_e32 v207, v105, v207
	s_waitcnt lgkmcnt(4)
	v_mfma_f32_32x32x16_bf16 v[48:63], v[202:205], v[64:67], v[48:63]
	v_add_f32_e32 v179, v106, v179
	v_add_f32_e32 v207, v107, v207
	v_add_f32_e32 v179, v108, v179
	v_add_f32_e32 v207, v109, v207
	v_add_f32_e32 v179, v110, v179
	v_add_f32_e32 v207, v111, v207
	v_cvt_pk_bf16_f32 v96, v96, v97
	v_cvt_pk_bf16_f32 v97, v98, v99
	v_cvt_pk_bf16_f32 v98, v100, v101
	v_cvt_pk_bf16_f32 v99, v102, v103
	v_cvt_pk_bf16_f32 v100, v104, v105
	v_cvt_pk_bf16_f32 v101, v106, v107
	v_cvt_pk_bf16_f32 v102, v108, v109
	v_cvt_pk_bf16_f32 v103, v110, v111
	v_mfma_f32_32x32x16_bf16 v[16:31], v[202:205], v[96:99], v[16:31]
	ds_read_b64_tr_b16 v[224:225], v232 offset:2560
	ds_read_b64_tr_b16 v[226:227], v232 offset:3584
	v_exp_f32_e32 v80, v80
	v_exp_f32_e32 v81, v81
	v_exp_f32_e32 v82, v82
	v_exp_f32_e32 v83, v83
	v_exp_f32_e32 v84, v84
	v_exp_f32_e32 v85, v85
	v_exp_f32_e32 v86, v86
	v_exp_f32_e32 v87, v87
	s_waitcnt lgkmcnt(4)
	v_mfma_f32_32x32x16_bf16 v[32:47], v[210:213], v[64:67], v[32:47]
	v_exp_f32_e32 v88, v88
	v_exp_f32_e32 v89, v89
	v_exp_f32_e32 v90, v90
	v_exp_f32_e32 v91, v91
	v_exp_f32_e32 v92, v92
	v_exp_f32_e32 v93, v93
	v_exp_f32_e32 v94, v94
	v_exp_f32_e32 v95, v95
	v_mfma_f32_32x32x16_bf16 v[0:15], v[210:213], v[96:99], v[0:15]
	ds_read_b64_tr_b16 v[202:203], v232 offset:4096
	ds_read_b64_tr_b16 v[204:205], v232 offset:5120
	v_add_f32_e32 v178, v80, v178
	v_add_f32_e32 v206, v81, v206
	v_add_f32_e32 v178, v82, v178
	v_add_f32_e32 v206, v83, v206
	v_add_f32_e32 v178, v84, v178
	v_add_f32_e32 v206, v85, v206
	v_add_f32_e32 v178, v86, v178
	v_add_f32_e32 v206, v87, v206
	s_waitcnt lgkmcnt(4)
	v_mfma_f32_32x32x16_bf16 v[48:63], v[220:223], v[68:71], v[48:63]
	v_add_f32_e32 v178, v88, v178
	v_add_f32_e32 v206, v89, v206
	v_add_f32_e32 v178, v90, v178
	v_add_f32_e32 v206, v91, v206
	v_add_f32_e32 v178, v92, v178
	v_add_f32_e32 v206, v93, v206
	v_add_f32_e32 v178, v94, v178
	v_add_f32_e32 v206, v95, v206
	v_mfma_f32_32x32x16_bf16 v[16:31], v[220:223], v[100:103], v[16:31]
	ds_read_b64_tr_b16 v[210:211], v232 offset:4608
	ds_read_b64_tr_b16 v[212:213], v232 offset:5632
	v_cvt_pk_bf16_f32 v80, v80, v81
	v_cvt_pk_bf16_f32 v81, v82, v83
	v_cvt_pk_bf16_f32 v82, v84, v85
	v_cvt_pk_bf16_f32 v83, v86, v87
	v_cvt_pk_bf16_f32 v84, v88, v89
	v_cvt_pk_bf16_f32 v85, v90, v91
	v_cvt_pk_bf16_f32 v86, v92, v93
	v_cvt_pk_bf16_f32 v87, v94, v95
	s_waitcnt lgkmcnt(4)
	v_mfma_f32_32x32x16_bf16 v[32:47], v[224:227], v[68:71], v[32:47]
	v_exp_f32_e32 v112, v112
	v_exp_f32_e32 v113, v113
	v_exp_f32_e32 v114, v114
	v_exp_f32_e32 v115, v115
	v_exp_f32_e32 v116, v116
	v_exp_f32_e32 v117, v117
	v_exp_f32_e32 v118, v118
	v_exp_f32_e32 v119, v119
	v_mfma_f32_32x32x16_bf16 v[0:15], v[224:227], v[100:103], v[0:15]
	ds_read_b64_tr_b16 v[220:221], v232 offset:6144
	ds_read_b64_tr_b16 v[222:223], v232 offset:7168
	v_exp_f32_e32 v120, v120
	v_exp_f32_e32 v121, v121
	v_exp_f32_e32 v122, v122
	v_exp_f32_e32 v123, v123
	v_exp_f32_e32 v124, v124
	v_exp_f32_e32 v125, v125
	v_exp_f32_e32 v126, v126
	v_exp_f32_e32 v127, v127
	s_waitcnt lgkmcnt(4)
	v_mfma_f32_32x32x16_bf16 v[48:63], v[202:205], v[80:83], v[48:63]
	v_add_f32_e32 v179, v112, v179
	v_add_f32_e32 v207, v113, v207
	v_add_f32_e32 v179, v114, v179
	v_add_f32_e32 v207, v115, v207
	v_add_f32_e32 v179, v116, v179
	v_add_f32_e32 v207, v117, v207
	v_add_f32_e32 v179, v118, v179
	v_add_f32_e32 v207, v119, v207
	v_add_f32_e32 v179, v120, v179
	v_add_f32_e32 v207, v121, v207
	v_add_f32_e32 v179, v122, v179
	v_add_f32_e32 v207, v123, v207
	v_add_f32_e32 v179, v124, v179
	v_add_f32_e32 v207, v125, v207
	v_add_f32_e32 v179, v126, v179
	v_add_f32_e32 v207, v127, v207
	v_cvt_pk_bf16_f32 v112, v112, v113
	v_cvt_pk_bf16_f32 v113, v114, v115
	v_cvt_pk_bf16_f32 v114, v116, v117
	v_cvt_pk_bf16_f32 v115, v118, v119
	v_cvt_pk_bf16_f32 v116, v120, v121
	v_cvt_pk_bf16_f32 v117, v122, v123
	v_cvt_pk_bf16_f32 v118, v124, v125
	v_cvt_pk_bf16_f32 v119, v126, v127
	v_mfma_f32_32x32x16_bf16 v[16:31], v[202:205], v[112:115], v[16:31]
	ds_read_b64_tr_b16 v[224:225], v232 offset:6656
	ds_read_b64_tr_b16 v[226:227], v232 offset:7680
	s_waitcnt lgkmcnt(4)
	v_mfma_f32_32x32x16_bf16 v[32:47], v[210:213], v[80:83], v[32:47]
	v_mfma_f32_32x32x16_bf16 v[0:15], v[210:213], v[112:115], v[0:15]
	s_waitcnt lgkmcnt(2)
	v_mfma_f32_32x32x16_bf16 v[48:63], v[220:223], v[84:87], v[48:63]
	v_mfma_f32_32x32x16_bf16 v[16:31], v[220:223], v[116:119], v[16:31]
	s_waitcnt lgkmcnt(0)
	v_mfma_f32_32x32x16_bf16 v[32:47], v[224:227], v[84:87], v[32:47]
	v_mfma_f32_32x32x16_bf16 v[0:15], v[224:227], v[116:119], v[0:15]
	s_nop 7
	v_add_f32_e32 v178, v178, v206
	v_add_f32_e32 v179, v179, v207
	s_nop 3
	s_branch .LBB0_488
